# role swap: waves 0-3 high priority with late LDS-DMA burst (after G2), waves 4-7 burst at loop top
# speedup vs baseline: 1.0046x; 1.0046x over previous
.LBB0_3:
	s_load_dwordx2 s[74:75], s[0:1], 0x110
	s_load_dwordx4 s[88:91], s[0:1], 0x100
	s_load_dwordx16 s[36:51], s[0:1], 0x0
	s_load_dwordx16 s[4:19], s[0:1], 0x40
	s_lshl_b32 s70, s72, 1
	v_lshrrev_b32_e32 v1, 20, v0
	v_lshrrev_b32_e32 v0, 10, v0
	v_or_b32_e32 v0, v0, v1
	s_waitcnt lgkmcnt(0)
	v_writelane_b32 v254, s4, 6
	s_movk_i32 s73, 0x3ff
	v_and_or_b32 v0, v0, s73, v190
	v_writelane_b32 v254, s5, 7
	v_writelane_b32 v254, s6, 8
	v_writelane_b32 v254, s7, 9
	v_writelane_b32 v254, s8, 10
	v_writelane_b32 v254, s9, 11
	v_writelane_b32 v254, s10, 12
	v_writelane_b32 v254, s11, 13
	v_writelane_b32 v254, s12, 14
	v_writelane_b32 v254, s13, 15
	v_writelane_b32 v254, s14, 16
	v_writelane_b32 v254, s15, 17
	v_writelane_b32 v254, s16, 18
	v_writelane_b32 v254, s17, 19
	v_writelane_b32 v254, s18, 20
	v_writelane_b32 v254, s19, 21
	s_load_dwordx16 s[4:19], s[0:1], 0x80
	v_cmp_eq_u32_e64 s[2:3], 0, v0
	v_and_b32_e32 v191, 0xff, v190
	s_movk_i32 s71, 0x100
	v_mov_b32_e32 v145, 0
	s_waitcnt lgkmcnt(0)
	v_writelane_b32 v254, s4, 22
	s_mov_b32 s69, 0xfffc0000
	v_mov_b32_e32 v192, 0x358637bd
	v_writelane_b32 v254, s5, 23
	v_writelane_b32 v254, s6, 24
	v_writelane_b32 v254, s7, 25
	v_writelane_b32 v254, s8, 26
	v_writelane_b32 v254, s9, 27
	v_writelane_b32 v254, s10, 28
	v_writelane_b32 v254, s11, 29
	v_writelane_b32 v254, s12, 30
	v_writelane_b32 v254, s13, 31
	v_writelane_b32 v254, s14, 32
	v_writelane_b32 v254, s15, 33
	v_writelane_b32 v254, s16, 34
	v_writelane_b32 v254, s17, 35
	v_writelane_b32 v254, s18, 36
	v_writelane_b32 v254, s19, 37
	s_load_dwordx16 s[4:19], s[0:1], 0xc0
	s_lshl_b32 s0, s79, 1
	s_movk_i32 s85, 0x5800
	s_mov_b32 s81, 0x10000
	s_mov_b32 s78, 0x20000
	s_waitcnt lgkmcnt(0)
	v_writelane_b32 v254, s4, 38
	s_movk_i32 s33, 0x1600
	s_movk_i32 s83, 0x7fff
	v_writelane_b32 v254, s5, 39
	v_writelane_b32 v254, s6, 40
	v_writelane_b32 v254, s7, 41
	v_writelane_b32 v254, s8, 42
	v_writelane_b32 v254, s9, 43
	v_writelane_b32 v254, s10, 44
	v_writelane_b32 v254, s11, 45
	v_writelane_b32 v254, s12, 46
	v_writelane_b32 v254, s13, 47
	v_writelane_b32 v254, s14, 48
	v_writelane_b32 v254, s15, 49
	v_writelane_b32 v254, s16, 50
	v_writelane_b32 v254, s17, 51
	v_writelane_b32 v254, s18, 52
	v_writelane_b32 v254, s19, 53
	s_lshl_b32 s4, s72, 3
	s_cmpk_lt_i32 s79, 0x100
	v_writelane_b32 v254, s0, 54
	s_cselect_b64 s[0:1], -1, 0
	v_writelane_b32 v254, s0, 55
	s_cmpk_lt_i32 s79, 0x200
	v_mov_b32_e32 v193, 0x3ecc95a3
	v_writelane_b32 v254, s1, 56
	s_cselect_b64 s[0:1], -1, 0
	v_writelane_b32 v254, s0, 57
	s_mov_b32 s82, 0x3db8aa3b
	s_mov_b64 s[86:87], 0x20000
	v_writelane_b32 v254, s1, 58
	s_add_i32 s0, s70, 0xbff
	v_writelane_b32 v254, s0, 59
	s_add_i32 s0, s70, 0x9ff
	s_cmpk_lt_i32 s79, 0x5c0
	v_writelane_b32 v254, s0, 60
	s_cselect_b64 s[0:1], -1, 0
	v_writelane_b32 v254, s0, 61
	s_ashr_i32 s5, s4, 31
	s_mov_b64 s[10:11], 0x80
	v_writelane_b32 v254, s1, 62
	v_cmp_gt_u32_e64 s[0:1], 64, v190
	s_mov_b64 s[92:93], 0x40080
	s_mov_b64 s[94:95], 0x60080
	v_writelane_b32 v254, s0, 63
	s_mov_b32 s76, 0x3e38aa3b
	v_mov_b32_e32 v195, 0x3c088889
	v_writelane_b32 v255, s1, 0
	v_writelane_b32 v255, s2, 1
	s_bfe_i32 s0, s72, 0x1001e
	s_mov_b32 s1, 0
	v_writelane_b32 v255, s3, 2
	v_writelane_b32 v255, s0, 3
	s_abs_i32 s0, s70
	v_cvt_f32_u32_e32 v0, s0
	v_writelane_b32 v255, s0, 4
	s_sub_i32 s0, 0, s0
	s_mov_b32 s84, 0xbe800000
	v_rcp_iflag_f32_e32 v0, v0
	v_mov_b32_e32 v197, 0x3c0881c4
	v_mov_b32_e32 v198, 0xbab64f3b
	v_mov_b32_e32 v200, 0x21004
	v_mul_f32_e32 v0, 0x4f7ffffe, v0
	v_cvt_u32_f32_e32 v0, v0
	v_mov_b32_e32 v201, 1
	v_mov_b64_e32 v[252:253], 0x40000
	v_mov_b32_e32 v202, 0x7f800000
	v_readfirstlane_b32 s2, v0
	s_mul_i32 s0, s0, s2
	s_mul_hi_u32 s0, s2, s0
	s_add_i32 s0, s2, s0
	v_writelane_b32 v255, s0, 5
	v_writelane_b32 v255, s4, 6
	s_lshl_b64 s[2:3], s[4:5], 2
	v_mov_b32_e32 v150, 0x3f317218
	v_writelane_b32 v255, s5, 7
	v_writelane_b32 v255, s2, 8
	v_mbcnt_lo_u32_b32 v0, -1, 0
	v_mbcnt_hi_u32_b32 v194, -1, v0
	v_writelane_b32 v255, s3, 9
	s_add_u32 s2, s90, 0xc00
	s_addc_u32 s3, s91, 0
	v_writelane_b32 v255, s2, 10
	s_lshl_b32 s0, s79, 9
	v_mov_b32_e32 v203, 2
	v_writelane_b32 v255, s3, 11
	s_lshl_b64 s[2:3], s[4:5], 12
	v_writelane_b32 v255, s2, 12
	v_mov_b32_e32 v204, 0x20000
	v_mov_b32_e32 v205, 0x20800
	v_writelane_b32 v255, s3, 13
	v_writelane_b32 v255, s0, 14
	s_lshl_b32 s0, s72, 9
	v_writelane_b32 v255, s0, 15
	s_lshl_b32 s0, s79, 17
	v_writelane_b32 v255, s0, 16
	s_lshl_b32 s0, s72, 17
	v_writelane_b32 v255, s0, 17
	s_lshl_b32 s0, s79, 3
	v_writelane_b32 v255, s0, 18
	s_lshl_b32 s0, s79, 19
	v_writelane_b32 v255, s0, 19
	s_lshl_b32 s0, s72, 19
	v_writelane_b32 v255, s0, 20
	s_lshl_b64 s[2:3], s[4:5], 11
	v_writelane_b32 v255, s2, 21
	s_mov_b64 s[4:5], 0x20080
	v_mov_b32_e32 v196, 0xfffffe00
	v_writelane_b32 v255, s3, 22
	v_writelane_b32 v255, s72, 23
	v_writelane_b32 v255, s74, 24
	v_readlane_b32 s2, v254, 0
	v_mov_b32_e32 v211, 0x50
	v_writelane_b32 v255, s75, 25
	v_writelane_b32 v255, s70, 26
	v_writelane_b32 v255, s36, 27
	v_mov_b32_e32 v212, 0x60
	v_mov_b32_e32 v199, 0x70
	v_writelane_b32 v255, s37, 28
	v_writelane_b32 v255, s38, 29
	v_writelane_b32 v255, s39, 30
	v_writelane_b32 v255, s40, 31
	v_writelane_b32 v255, s41, 32
	v_writelane_b32 v255, s42, 33
	v_writelane_b32 v255, s43, 34
	v_writelane_b32 v255, s44, 35
	v_writelane_b32 v255, s45, 36
	v_writelane_b32 v255, s46, 37
	v_writelane_b32 v255, s47, 38
	v_writelane_b32 v255, s48, 39
	v_writelane_b32 v255, s49, 40
	v_writelane_b32 v255, s50, 41
	v_mov_b32_e32 v210, 0x160000
	v_not_b32_e32 v213, 63
	v_not_b32_e32 v214, 31
	v_mov_b32_e32 v215, 0x7fc00000
	s_mov_b32 s96, s2
	v_writelane_b32 v255, s51, 42
	v_readfirstlane_b32 s98, v190
	s_nop 3
	s_cmpk_ge_u32 s98, 0x100
	s_cbranch_scc1 .Lprio_done
	s_setprio 1

.LBB0_237:
	s_or_b64 exec, exec, s[2:3]
	s_ashr_i32 s3, s9, 2
	s_lshr_b32 s2, s30, 3
	s_lshl_b32 s36, s3, 2
	s_ashr_i32 s23, s22, 31
	s_and_b32 s7, s29, 56
	s_and_b32 s31, s2, 3
	s_sub_i32 s8, s8, s36
	s_lshl_b64 s[2:3], s[22:23], 19
	s_add_u32 s2, s16, s2
	s_addc_u32 s3, s17, s3
	s_ashr_i32 s9, s8, 31
	v_mov_b32_e32 v8, v190
	s_lshl_b64 s[22:23], s[8:9], 19
	s_mov_b32 s9, 0x1ffff80
	v_and_b32_e32 v0, 15, v8
	v_lshrrev_b32_e32 v2, 1, v8
	v_and_or_b32 v0, v2, s9, v0
	v_bfe_u32 v1, v8, 4, 2
	v_lshlrev_b32_e32 v132, 7, v0
	v_bfe_u32 v0, v8, 1, 3
	v_bitop3_b32 v0, v1, v0, 4 bitop3:0x36
	v_lshlrev_b32_e32 v133, 4, v0
	v_lshlrev_b32_e32 v0, 7, v8
	v_and_b32_e32 v134, 0x6780, v0
	v_ashrrev_i32_e32 v0, 3, v8
	v_bitop3_b32 v2, v2, v1, 7 bitop3:0x6c
	v_ashrrev_i32_e32 v1, 31, v0
	v_lshrrev_b32_e32 v9, 4, v8
	v_lshlrev_b64 v[0:1], 11, v[0:1]
	s_add_u32 s34, s25, s22
	v_lshlrev_b32_e32 v135, 4, v2
	v_xor_b32_e32 v4, v9, v8
	v_lshl_add_u64 v[2:3], s[2:3], 0, v[0:1]
	v_readfirstlane_b32 s2, v8
	s_addc_u32 s35, s26, s23
	v_lshlrev_b32_e32 v4, 4, v4
	s_lshl_b32 s2, s2, 4
	v_and_b32_e32 v144, 0x70, v4
	s_and_b32 s2, s2, 0xfffffc00
	v_lshl_add_u64 v[2:3], v[2:3], 0, v[144:145]
	s_mov_b32 m0, s2
	s_mov_b64 s[38:39], 0x20000
	v_lshl_add_u64 v[4:5], s[34:35], 0, v[0:1]
	s_waitcnt lgkmcnt(0)
	s_barrier
	global_load_lds_dwordx4 v[2:3], off
	v_lshl_add_u64 v[6:7], v[2:3], 0, s[38:39]
	s_add_i32 m0, s2, 0x2000
	s_mov_b64 s[34:35], 0x40000
	global_load_lds_dwordx4 v[6:7], off
	v_lshl_add_u64 v[6:7], v[2:3], 0, s[34:35]
	s_add_i32 m0, s2, 0x4000
	s_mov_b64 s[40:41], 0x60000
	global_load_lds_dwordx4 v[6:7], off
	v_lshl_add_u64 v[2:3], v[2:3], 0, s[40:41]
	s_add_i32 m0, s2, 0x6000
	v_lshl_add_u64 v[4:5], v[4:5], 0, v[144:145]
	global_load_lds_dwordx4 v[2:3], off
	s_add_i32 m0, s2, 0x8000
	v_lshl_add_u64 v[2:3], v[4:5], 0, s[38:39]
	global_load_lds_dwordx4 v[4:5], off
	s_add_i32 m0, s2, 0xa000
	s_add_i32 s7, s7, s36
	global_load_lds_dwordx4 v[2:3], off
	v_lshl_add_u64 v[2:3], v[4:5], 0, s[34:35]
	s_add_i32 m0, s2, 0xc000
	v_mov_b32_e32 v88, 0
	global_load_lds_dwordx4 v[2:3], off
	v_lshl_add_u64 v[2:3], v[4:5], 0, s[40:41]
	s_add_i32 m0, s2, 0xe000
	v_bitop3_b32 v4, v9, 7, v8 bitop3:0x48
	global_load_lds_dwordx4 v[2:3], off
	v_lshl_add_u64 v[2:3], s[22:23], 0, v[0:1]
	s_or_b32 s22, s7, s31
	s_ashr_i32 s23, s22, 31
	s_lshl_b64 s[22:23], s[22:23], 19
	s_waitcnt vmcnt(0)
	v_lshlrev_b32_e32 v4, 4, v4
	v_lshl_add_u64 v[0:1], s[22:23], 0, v[0:1]
	v_or_b32_e32 v2, v2, v4
	v_or_b32_e32 v0, v0, v4
	s_mov_b64 s[86:87], 0x20000
	v_lshl_add_u64 v[128:129], s[14:15], 0, v[2:3]
	v_lshl_add_u64 v[130:131], s[14:15], 0, v[0:1]
	s_mov_b64 s[22:23], 0
	s_mov_b32 s3, 0
	v_mov_b32_e32 v89, v88
	v_mov_b32_e32 v90, v88
	v_mov_b32_e32 v91, v88
	v_mov_b32_e32 v0, v88
	v_mov_b32_e32 v1, v88
	v_mov_b32_e32 v2, v88
	v_mov_b32_e32 v3, v88
	v_mov_b32_e32 v4, v88
	v_mov_b32_e32 v5, v88
	v_mov_b32_e32 v6, v88
	v_mov_b32_e32 v7, v88
	v_mov_b32_e32 v8, v88
	v_mov_b32_e32 v9, v88
	v_mov_b32_e32 v10, v88
	v_mov_b32_e32 v11, v88
	v_mov_b32_e32 v12, v88
	v_mov_b32_e32 v13, v88
	v_mov_b32_e32 v14, v88
	v_mov_b32_e32 v15, v88
	v_mov_b32_e32 v16, v88
	v_mov_b32_e32 v17, v88
	v_mov_b32_e32 v18, v88
	v_mov_b32_e32 v19, v88
	v_mov_b32_e32 v20, v88
	v_mov_b32_e32 v21, v88
	v_mov_b32_e32 v22, v88
	v_mov_b32_e32 v23, v88
	v_mov_b32_e32 v24, v88
	v_mov_b32_e32 v25, v88
	v_mov_b32_e32 v26, v88
	v_mov_b32_e32 v27, v88
	v_mov_b32_e32 v28, v88
	v_mov_b32_e32 v29, v88
	v_mov_b32_e32 v30, v88
	v_mov_b32_e32 v31, v88
	v_mov_b32_e32 v32, v88
	v_mov_b32_e32 v33, v88
	v_mov_b32_e32 v34, v88
	v_mov_b32_e32 v35, v88
	v_mov_b32_e32 v36, v88
	v_mov_b32_e32 v37, v88
	v_mov_b32_e32 v38, v88
	v_mov_b32_e32 v39, v88
	v_mov_b32_e32 v40, v88
	v_mov_b32_e32 v41, v88
	v_mov_b32_e32 v42, v88
	v_mov_b32_e32 v43, v88
	v_mov_b32_e32 v44, v88
	v_mov_b32_e32 v45, v88
	v_mov_b32_e32 v46, v88
	v_mov_b32_e32 v47, v88
	v_mov_b32_e32 v48, v88
	v_mov_b32_e32 v49, v88
	v_mov_b32_e32 v50, v88
	v_mov_b32_e32 v51, v88
	v_mov_b32_e32 v52, v88
	v_mov_b32_e32 v53, v88
	v_mov_b32_e32 v54, v88
	v_mov_b32_e32 v55, v88
	v_mov_b32_e32 v56, v88
	v_mov_b32_e32 v57, v88
	v_mov_b32_e32 v58, v88
	v_mov_b32_e32 v59, v88
	v_mov_b32_e32 v60, v88
	v_mov_b32_e32 v61, v88
	v_mov_b32_e32 v62, v88
	v_mov_b32_e32 v63, v88
	v_mov_b32_e32 v64, v88
	v_mov_b32_e32 v65, v88
	v_mov_b32_e32 v66, v88
	v_mov_b32_e32 v67, v88
	v_mov_b32_e32 v68, v88
	v_mov_b32_e32 v69, v88
	v_mov_b32_e32 v70, v88
	v_mov_b32_e32 v71, v88
	v_mov_b32_e32 v72, v88
	v_mov_b32_e32 v73, v88
	v_mov_b32_e32 v74, v88
	v_mov_b32_e32 v75, v88
	v_mov_b32_e32 v76, v88
	v_mov_b32_e32 v77, v88
	v_mov_b32_e32 v78, v88
	v_mov_b32_e32 v79, v88
	v_mov_b32_e32 v80, v88
	v_mov_b32_e32 v81, v88
	v_mov_b32_e32 v82, v88
	v_mov_b32_e32 v83, v88
	v_mov_b32_e32 v84, v88
	v_mov_b32_e32 v85, v88
	v_mov_b32_e32 v86, v88
	v_mov_b32_e32 v87, v88
	v_mov_b32_e32 v92, v88
	v_mov_b32_e32 v93, v88
	v_mov_b32_e32 v94, v88
	v_mov_b32_e32 v95, v88
	v_mov_b32_e32 v96, v88
	v_mov_b32_e32 v97, v88
	v_mov_b32_e32 v98, v88
	v_mov_b32_e32 v99, v88
	v_mov_b32_e32 v100, v88
	v_mov_b32_e32 v101, v88
	v_mov_b32_e32 v102, v88
	v_mov_b32_e32 v103, v88
	v_mov_b32_e32 v104, v88
	v_mov_b32_e32 v105, v88
	v_mov_b32_e32 v106, v88
	v_mov_b32_e32 v107, v88
	v_mov_b32_e32 v108, v88
	v_mov_b32_e32 v109, v88
	v_mov_b32_e32 v110, v88
	v_mov_b32_e32 v111, v88
	v_mov_b32_e32 v112, v88
	v_mov_b32_e32 v113, v88
	v_mov_b32_e32 v114, v88
	v_mov_b32_e32 v115, v88
	v_mov_b32_e32 v116, v88
	v_mov_b32_e32 v117, v88
	v_mov_b32_e32 v118, v88
	v_mov_b32_e32 v119, v88
	v_mov_b32_e32 v120, v88
	v_mov_b32_e32 v121, v88
	v_mov_b32_e32 v122, v88
	v_mov_b32_e32 v123, v88
	v_mov_b32_e32 v124, v88
	v_mov_b32_e32 v125, v88
	v_mov_b32_e32 v126, v88
	v_mov_b32_e32 v127, v88
	s_mov_b64 s[36:37], 0x3a20080
	s_mov_b64 s[38:39], 0x3a40080
	s_waitcnt vmcnt(0) lgkmcnt(0)
	s_barrier
	s_bitcmp1_b32 s2, 12
	s_cbranch_scc0 .Lkb_238

.LBB0_245:
	s_ashr_i32 s2, s28, 5
	s_lshr_b32 s3, s2, 30
	s_add_i32 s3, s2, s3
	s_and_b32 s31, s3, -4
	s_sub_i32 s18, s2, s31
	s_lshl_b32 s2, s28, 3
	s_and_b32 s2, s2, 56
	s_bfe_u32 s30, s28, 0x20003
	s_add_i32 s2, s31, s2
	s_or_b32 s22, s2, s30
	s_ashr_i32 s23, s22, 31
	s_and_b32 s29, s27, 56
	s_lshl_b64 s[2:3], s[22:23], 19
	s_add_u32 s2, s6, s2
	s_addc_u32 s3, s7, s3
	s_ashr_i32 s19, s18, 31
	v_mov_b32_e32 v6, v190
	s_lshl_b64 s[24:25], s[18:19], 19
	s_mov_b32 s19, 0x1ffff80
	v_and_b32_e32 v0, 15, v6
	v_lshrrev_b32_e32 v2, 1, v6
	v_and_or_b32 v0, v2, s19, v0
	s_waitcnt lgkmcnt(0)
	v_bfe_u32 v1, v6, 4, 2
	v_lshlrev_b32_e32 v132, 7, v0
	v_bfe_u32 v0, v6, 1, 3
	v_bitop3_b32 v0, v1, v0, 4 bitop3:0x36
	v_lshlrev_b32_e32 v133, 4, v0
	v_lshlrev_b32_e32 v0, 7, v6
	v_and_b32_e32 v134, 0x6780, v0
	v_ashrrev_i32_e32 v0, 3, v6
	v_bitop3_b32 v2, v2, v1, 7 bitop3:0x6c
	v_ashrrev_i32_e32 v1, 31, v0
	v_lshrrev_b32_e32 v7, 4, v6
	v_lshlrev_b64 v[0:1], 11, v[0:1]
	s_add_u32 s24, s0, s24
	v_lshlrev_b32_e32 v135, 4, v2
	v_xor_b32_e32 v4, v7, v6
	v_lshl_add_u64 v[2:3], s[2:3], 0, v[0:1]
	v_readfirstlane_b32 s2, v6
	s_addc_u32 s25, s26, s25
	v_lshlrev_b32_e32 v4, 4, v4
	s_lshl_b32 s2, s2, 4
	v_and_b32_e32 v144, 0x70, v4
	s_and_b32 s2, s2, 0xfffffc00
	v_lshl_add_u64 v[2:3], v[2:3], 0, v[144:145]
	v_lshl_add_u64 v[4:5], s[24:25], 0, v[0:1]
	s_mov_b32 m0, s2
	s_mov_b64 s[34:35], 0x20000
	v_lshl_add_u64 v[128:129], v[4:5], 0, v[144:145]
	s_waitcnt lgkmcnt(0)
	s_barrier
	global_load_lds_dwordx4 v[2:3], off
	v_lshl_add_u64 v[4:5], v[2:3], 0, s[34:35]
	s_add_i32 m0, s2, 0x2000
	s_mov_b64 s[24:25], 0x40000
	global_load_lds_dwordx4 v[4:5], off
	v_lshl_add_u64 v[4:5], v[2:3], 0, s[24:25]
	s_add_i32 m0, s2, 0x4000
	s_mov_b64 s[36:37], 0x60000
	global_load_lds_dwordx4 v[4:5], off
	v_lshl_add_u64 v[2:3], v[2:3], 0, s[36:37]
	s_add_i32 m0, s2, 0x6000
	s_add_i32 s29, s29, s31
	global_load_lds_dwordx4 v[2:3], off
	s_add_i32 m0, s2, 0x8000
	v_lshl_add_u64 v[2:3], v[128:129], 0, s[34:35]
	global_load_lds_dwordx4 v[128:129], off
	s_add_i32 m0, s2, 0xa000
	v_mov_b32_e32 v88, 0
	global_load_lds_dwordx4 v[2:3], off
	v_lshl_add_u64 v[2:3], v[128:129], 0, s[24:25]
	s_add_i32 m0, s2, 0xc000
	s_or_b32 s24, s29, s30
	global_load_lds_dwordx4 v[2:3], off
	v_lshl_add_u64 v[2:3], v[128:129], 0, s[36:37]
	s_add_i32 m0, s2, 0xe000
	s_ashr_i32 s25, s24, 31
	global_load_lds_dwordx4 v[2:3], off
	s_lshl_b64 s[24:25], s[24:25], 19
	s_waitcnt vmcnt(0)
	v_lshl_add_u64 v[0:1], s[24:25], 0, v[0:1]
	v_bitop3_b32 v2, v7, 7, v6 bitop3:0x48
	v_lshl_or_b32 v0, v2, 4, v0
	s_mov_b64 s[86:87], 0x20000
	v_lshl_add_u64 v[130:131], s[6:7], 0, v[0:1]
	s_mov_b64 s[24:25], 0
	s_mov_b32 s3, 0
	v_mov_b32_e32 v89, v88
	v_mov_b32_e32 v90, v88
	v_mov_b32_e32 v91, v88
	v_mov_b32_e32 v0, v88
	v_mov_b32_e32 v1, v88
	v_mov_b32_e32 v2, v88
	v_mov_b32_e32 v3, v88
	v_mov_b32_e32 v4, v88
	v_mov_b32_e32 v5, v88
	v_mov_b32_e32 v6, v88
	v_mov_b32_e32 v7, v88
	v_mov_b32_e32 v8, v88
	v_mov_b32_e32 v9, v88
	v_mov_b32_e32 v10, v88
	v_mov_b32_e32 v11, v88
	v_mov_b32_e32 v12, v88
	v_mov_b32_e32 v13, v88
	v_mov_b32_e32 v14, v88
	v_mov_b32_e32 v15, v88
	v_mov_b32_e32 v16, v88
	v_mov_b32_e32 v17, v88
	v_mov_b32_e32 v18, v88
	v_mov_b32_e32 v19, v88
	v_mov_b32_e32 v20, v88
	v_mov_b32_e32 v21, v88
	v_mov_b32_e32 v22, v88
	v_mov_b32_e32 v23, v88
	v_mov_b32_e32 v24, v88
	v_mov_b32_e32 v25, v88
	v_mov_b32_e32 v26, v88
	v_mov_b32_e32 v27, v88
	v_mov_b32_e32 v28, v88
	v_mov_b32_e32 v29, v88
	v_mov_b32_e32 v30, v88
	v_mov_b32_e32 v31, v88
	v_mov_b32_e32 v32, v88
	v_mov_b32_e32 v33, v88
	v_mov_b32_e32 v34, v88
	v_mov_b32_e32 v35, v88
	v_mov_b32_e32 v36, v88
	v_mov_b32_e32 v37, v88
	v_mov_b32_e32 v38, v88
	v_mov_b32_e32 v39, v88
	v_mov_b32_e32 v40, v88
	v_mov_b32_e32 v41, v88
	v_mov_b32_e32 v42, v88
	v_mov_b32_e32 v43, v88
	v_mov_b32_e32 v44, v88
	v_mov_b32_e32 v45, v88
	v_mov_b32_e32 v46, v88
	v_mov_b32_e32 v47, v88
	v_mov_b32_e32 v48, v88
	v_mov_b32_e32 v49, v88
	v_mov_b32_e32 v50, v88
	v_mov_b32_e32 v51, v88
	v_mov_b32_e32 v52, v88
	v_mov_b32_e32 v53, v88
	v_mov_b32_e32 v54, v88
	v_mov_b32_e32 v55, v88
	v_mov_b32_e32 v56, v88
	v_mov_b32_e32 v57, v88
	v_mov_b32_e32 v58, v88
	v_mov_b32_e32 v59, v88
	v_mov_b32_e32 v60, v88
	v_mov_b32_e32 v61, v88
	v_mov_b32_e32 v62, v88
	v_mov_b32_e32 v63, v88
	v_mov_b32_e32 v64, v88
	v_mov_b32_e32 v65, v88
	v_mov_b32_e32 v66, v88
	v_mov_b32_e32 v67, v88
	v_mov_b32_e32 v68, v88
	v_mov_b32_e32 v69, v88
	v_mov_b32_e32 v70, v88
	v_mov_b32_e32 v71, v88
	v_mov_b32_e32 v72, v88
	v_mov_b32_e32 v73, v88
	v_mov_b32_e32 v74, v88
	v_mov_b32_e32 v75, v88
	v_mov_b32_e32 v76, v88
	v_mov_b32_e32 v77, v88
	v_mov_b32_e32 v78, v88
	v_mov_b32_e32 v79, v88
	v_mov_b32_e32 v80, v88
	v_mov_b32_e32 v81, v88
	v_mov_b32_e32 v82, v88
	v_mov_b32_e32 v83, v88
	v_mov_b32_e32 v84, v88
	v_mov_b32_e32 v85, v88
	v_mov_b32_e32 v86, v88
	v_mov_b32_e32 v87, v88
	v_mov_b32_e32 v92, v88
	v_mov_b32_e32 v93, v88
	v_mov_b32_e32 v94, v88
	v_mov_b32_e32 v95, v88
	v_mov_b32_e32 v96, v88
	v_mov_b32_e32 v97, v88
	v_mov_b32_e32 v98, v88
	v_mov_b32_e32 v99, v88
	v_mov_b32_e32 v100, v88
	v_mov_b32_e32 v101, v88
	v_mov_b32_e32 v102, v88
	v_mov_b32_e32 v103, v88
	v_mov_b32_e32 v104, v88
	v_mov_b32_e32 v105, v88
	v_mov_b32_e32 v106, v88
	v_mov_b32_e32 v107, v88
	v_mov_b32_e32 v108, v88
	v_mov_b32_e32 v109, v88
	v_mov_b32_e32 v110, v88
	v_mov_b32_e32 v111, v88
	v_mov_b32_e32 v112, v88
	v_mov_b32_e32 v113, v88
	v_mov_b32_e32 v114, v88
	v_mov_b32_e32 v115, v88
	v_mov_b32_e32 v116, v88
	v_mov_b32_e32 v117, v88
	v_mov_b32_e32 v118, v88
	v_mov_b32_e32 v119, v88
	v_mov_b32_e32 v120, v88
	v_mov_b32_e32 v121, v88
	v_mov_b32_e32 v122, v88
	v_mov_b32_e32 v123, v88
	v_mov_b32_e32 v124, v88
	v_mov_b32_e32 v125, v88
	v_mov_b32_e32 v126, v88
	v_mov_b32_e32 v127, v88
	s_waitcnt vmcnt(0) lgkmcnt(0)
	s_barrier
	s_bitcmp1_b32 s2, 12
	s_cbranch_scc0 .Lkb_246

.LBB0_419:
	v_and_b32_e32 v5, 15, v3
	v_lshrrev_b32_e32 v6, 1, v3
	s_mov_b32 s3, 0x1ffff80
	s_lshr_b32 s2, s57, 3
	v_and_or_b32 v5, v6, s3, v5
	s_and_b32 s3, s36, 56
	s_and_b32 s2, s2, 3
	s_add_i32 s3, s3, s61
	s_add_i32 s2, s3, s2
	v_and_b32_e32 v4, 3, v4
	v_lshlrev_b32_e32 v136, 7, v5
	v_bfe_u32 v5, v3, 1, 3
	s_ashr_i32 s3, s2, 31
	v_bitop3_b32 v6, v6, v4, 7 bitop3:0x6c
	v_bitop3_b32 v4, v4, v5, 4 bitop3:0x36
	v_lshlrev_b64 v[0:1], 11, v[0:1]
	v_lshlrev_b32_e32 v2, 4, v2
	s_lshl_b64 s[2:3], s[2:3], 19
	v_lshlrev_b32_e32 v137, 4, v4
	v_lshlrev_b32_e32 v3, 7, v3
	s_waitcnt vmcnt(0)
	v_lshl_add_u64 v[4:5], s[26:27], 0, v[0:1]
	v_and_b32_e32 v144, 0x70, v2
	v_lshl_add_u64 v[0:1], s[2:3], 0, v[0:1]
	v_and_b32_e32 v138, 0x6780, v3
	v_lshl_add_u64 v[2:3], v[4:5], 0, v[144:145]
	v_or_b32_e32 v0, v0, v144
	v_mov_b32_e32 v88, 0
	v_lshlrev_b32_e32 v139, 4, v6
	v_lshl_add_u64 v[132:133], s[14:15], 0, v[2:3]
	v_lshl_add_u64 v[134:135], s[14:15], 0, v[0:1]
	s_mov_b64 s[26:27], 0
	s_mov_b32 s2, 0
	v_mov_b32_e32 v89, v88
	v_mov_b32_e32 v90, v88
	v_mov_b32_e32 v91, v88
	v_mov_b32_e32 v0, v88
	v_mov_b32_e32 v1, v88
	v_mov_b32_e32 v2, v88
	v_mov_b32_e32 v3, v88
	v_mov_b32_e32 v4, v88
	v_mov_b32_e32 v5, v88
	v_mov_b32_e32 v6, v88
	v_mov_b32_e32 v7, v88
	v_mov_b32_e32 v8, v88
	v_mov_b32_e32 v9, v88
	v_mov_b32_e32 v10, v88
	v_mov_b32_e32 v11, v88
	v_mov_b32_e32 v12, v88
	v_mov_b32_e32 v13, v88
	v_mov_b32_e32 v14, v88
	v_mov_b32_e32 v15, v88
	v_mov_b32_e32 v16, v88
	v_mov_b32_e32 v17, v88
	v_mov_b32_e32 v18, v88
	v_mov_b32_e32 v19, v88
	v_mov_b32_e32 v20, v88
	v_mov_b32_e32 v21, v88
	v_mov_b32_e32 v22, v88
	v_mov_b32_e32 v23, v88
	v_mov_b32_e32 v24, v88
	v_mov_b32_e32 v25, v88
	v_mov_b32_e32 v26, v88
	v_mov_b32_e32 v27, v88
	v_mov_b32_e32 v28, v88
	v_mov_b32_e32 v29, v88
	v_mov_b32_e32 v30, v88
	v_mov_b32_e32 v31, v88
	v_mov_b32_e32 v32, v88
	v_mov_b32_e32 v33, v88
	v_mov_b32_e32 v34, v88
	v_mov_b32_e32 v35, v88
	v_mov_b32_e32 v36, v88
	v_mov_b32_e32 v37, v88
	v_mov_b32_e32 v38, v88
	v_mov_b32_e32 v39, v88
	v_mov_b32_e32 v40, v88
	v_mov_b32_e32 v41, v88
	v_mov_b32_e32 v42, v88
	v_mov_b32_e32 v43, v88
	v_mov_b32_e32 v44, v88
	v_mov_b32_e32 v45, v88
	v_mov_b32_e32 v46, v88
	v_mov_b32_e32 v47, v88
	v_mov_b32_e32 v48, v88
	v_mov_b32_e32 v49, v88
	v_mov_b32_e32 v50, v88
	v_mov_b32_e32 v51, v88
	v_mov_b32_e32 v52, v88
	v_mov_b32_e32 v53, v88
	v_mov_b32_e32 v54, v88
	v_mov_b32_e32 v55, v88
	v_mov_b32_e32 v56, v88
	v_mov_b32_e32 v57, v88
	v_mov_b32_e32 v58, v88
	v_mov_b32_e32 v59, v88
	v_mov_b32_e32 v60, v88
	v_mov_b32_e32 v61, v88
	v_mov_b32_e32 v62, v88
	v_mov_b32_e32 v63, v88
	v_mov_b32_e32 v64, v88
	v_mov_b32_e32 v65, v88
	v_mov_b32_e32 v66, v88
	v_mov_b32_e32 v67, v88
	v_mov_b32_e32 v68, v88
	v_mov_b32_e32 v69, v88
	v_mov_b32_e32 v70, v88
	v_mov_b32_e32 v71, v88
	v_mov_b32_e32 v72, v88
	v_mov_b32_e32 v73, v88
	v_mov_b32_e32 v74, v88
	v_mov_b32_e32 v75, v88
	v_mov_b32_e32 v76, v88
	v_mov_b32_e32 v77, v88
	v_mov_b32_e32 v78, v88
	v_mov_b32_e32 v79, v88
	v_mov_b32_e32 v80, v88
	v_mov_b32_e32 v81, v88
	v_mov_b32_e32 v82, v88
	v_mov_b32_e32 v83, v88
	v_mov_b32_e32 v84, v88
	v_mov_b32_e32 v85, v88
	v_mov_b32_e32 v86, v88
	v_mov_b32_e32 v87, v88
	v_mov_b32_e32 v92, v88
	v_mov_b32_e32 v93, v88
	v_mov_b32_e32 v94, v88
	v_mov_b32_e32 v95, v88
	v_mov_b32_e32 v96, v88
	v_mov_b32_e32 v97, v88
	v_mov_b32_e32 v98, v88
	v_mov_b32_e32 v99, v88
	v_mov_b32_e32 v100, v88
	v_mov_b32_e32 v101, v88
	v_mov_b32_e32 v102, v88
	v_mov_b32_e32 v103, v88
	v_mov_b32_e32 v104, v88
	v_mov_b32_e32 v105, v88
	v_mov_b32_e32 v106, v88
	v_mov_b32_e32 v107, v88
	v_mov_b32_e32 v108, v88
	v_mov_b32_e32 v109, v88
	v_mov_b32_e32 v110, v88
	v_mov_b32_e32 v111, v88
	v_mov_b32_e32 v112, v88
	v_mov_b32_e32 v113, v88
	v_mov_b32_e32 v114, v88
	v_mov_b32_e32 v115, v88
	v_mov_b32_e32 v116, v88
	v_mov_b32_e32 v117, v88
	v_mov_b32_e32 v118, v88
	v_mov_b32_e32 v119, v88
	v_mov_b32_e32 v120, v88
	v_mov_b32_e32 v121, v88
	v_mov_b32_e32 v122, v88
	v_mov_b32_e32 v123, v88
	v_mov_b32_e32 v124, v88
	v_mov_b32_e32 v125, v88
	v_mov_b32_e32 v126, v88
	v_mov_b32_e32 v127, v88
	s_mov_b64 s[38:39], 0x3a20080
	s_mov_b64 s[40:41], 0x3a40080
	s_waitcnt vmcnt(0) lgkmcnt(0)
	s_barrier
	s_bitcmp1_b32 s0, 12
	s_cbranch_scc0 .Lkb_420

.LBB0_499:
	s_ashr_i32 s2, s34, 5
	s_lshr_b32 s3, s2, 30
	s_add_i32 s3, s2, s3
	s_and_b32 s36, s3, -4
	s_sub_i32 s35, s2, s36
	s_lshl_b32 s2, s34, 3
	s_and_b32 s2, s2, 56
	s_bfe_u32 s27, s34, 0x20003
	s_add_i32 s2, s36, s2
	s_or_b32 s2, s2, s27
	s_and_b32 s26, s31, 56
	s_mul_i32 s6, s2, 0x160000
	s_mul_hi_i32 s3, s2, 0x160000
	s_add_u32 s6, s29, s6
	s_addc_u32 s7, s30, s3
	s_mul_i32 s3, s35, 0x160000
	s_ashr_i32 s9, s3, 31
	s_waitcnt vmcnt(0) lgkmcnt(0)
	v_mov_b32_e32 v4, v190
	s_add_u32 s8, s0, s3
	s_mov_b32 s3, 0x1ffff80
	v_and_b32_e32 v0, 15, v4
	v_lshrrev_b32_e32 v2, 1, v4
	v_and_or_b32 v0, v2, s3, v0
	v_bfe_u32 v1, v4, 4, 2
	v_lshlrev_b32_e32 v132, 7, v0
	v_bfe_u32 v0, v4, 1, 3
	v_lshrrev_b32_e32 v5, 4, v4
	v_bitop3_b32 v2, v2, v1, 7 bitop3:0x6c
	v_bitop3_b32 v0, v1, v0, 4 bitop3:0x36
	v_lshlrev_b32_e32 v135, 4, v2
	v_lshlrev_b32_e32 v133, 4, v0
	v_lshlrev_b32_e32 v0, 7, v4
	v_xor_b32_e32 v2, v5, v4
	v_readfirstlane_b32 s3, v4
	s_addc_u32 s9, s28, s9
	v_and_b32_e32 v134, 0x6780, v0
	v_ashrrev_i32_e32 v6, 3, v4
	v_mov_b64_e32 v[0:1], s[6:7]
	v_lshlrev_b32_e32 v2, 4, v2
	s_lshl_b32 s3, s3, 4
	v_mad_i64_i32 v[0:1], s[6:7], v6, s33, v[0:1]
	v_and_b32_e32 v144, 0x70, v2
	v_mov_b64_e32 v[2:3], s[8:9]
	s_and_b32 s3, s3, 0xfffffc00
	v_lshl_add_u64 v[0:1], v[0:1], 0, v[144:145]
	v_mad_i64_i32 v[2:3], s[6:7], v6, s33, v[2:3]
	s_mov_b32 m0, s3
	v_lshl_add_u64 v[128:129], v[2:3], 0, v[144:145]
	s_barrier
	global_load_lds_dwordx4 v[0:1], off
	v_lshl_add_u64 v[2:3], v[0:1], 0, s[54:55]
	s_add_i32 m0, s3, 0x2000
	s_add_i32 s26, s26, s36
	global_load_lds_dwordx4 v[2:3], off
	v_lshl_add_u64 v[2:3], v[0:1], 0, s[56:57]
	s_add_i32 m0, s3, 0x4000
	v_lshl_add_u64 v[0:1], v[0:1], 0, s[62:63]
	global_load_lds_dwordx4 v[2:3], off
	s_add_i32 m0, s3, 0x6000
	s_or_b32 s8, s26, s27
	global_load_lds_dwordx4 v[0:1], off
	s_add_i32 m0, s3, 0x8000
	v_lshl_add_u64 v[0:1], v[128:129], 0, s[54:55]
	global_load_lds_dwordx4 v[128:129], off
	s_add_i32 m0, s3, 0xa000
	v_bitop3_b32 v2, v5, 7, v4 bitop3:0x48
	global_load_lds_dwordx4 v[0:1], off
	v_lshl_add_u64 v[0:1], v[128:129], 0, s[56:57]
	s_add_i32 m0, s3, 0xc000
	v_mov_b32_e32 v88, 0
	global_load_lds_dwordx4 v[0:1], off
	v_lshl_add_u64 v[0:1], v[128:129], 0, s[62:63]
	s_add_i32 m0, s3, 0xe000
	v_mov_b32_e32 v89, v88
	global_load_lds_dwordx4 v[0:1], off
	v_mad_i64_i32 v[0:1], s[6:7], v6, s33, 0
	s_waitcnt vmcnt(0)
	v_mad_i64_i32 v[0:1], s[6:7], s8, v210, v[0:1]
	v_lshl_or_b32 v0, v2, 4, v0
	v_lshl_add_u64 v[130:131], s[14:15], 0, v[0:1]
	s_mov_b64 s[6:7], 0
	s_mov_b32 s8, 0
	v_mov_b32_e32 v90, v88
	v_mov_b32_e32 v91, v88
	v_mov_b32_e32 v0, v88
	v_mov_b32_e32 v1, v88
	v_mov_b32_e32 v2, v88
	v_mov_b32_e32 v3, v88
	v_mov_b32_e32 v4, v88
	v_mov_b32_e32 v5, v88
	v_mov_b32_e32 v6, v88
	v_mov_b32_e32 v7, v88
	v_mov_b32_e32 v8, v88
	v_mov_b32_e32 v9, v88
	v_mov_b32_e32 v10, v88
	v_mov_b32_e32 v11, v88
	v_mov_b32_e32 v12, v88
	v_mov_b32_e32 v13, v88
	v_mov_b32_e32 v14, v88
	v_mov_b32_e32 v15, v88
	v_mov_b32_e32 v16, v88
	v_mov_b32_e32 v17, v88
	v_mov_b32_e32 v18, v88
	v_mov_b32_e32 v19, v88
	v_mov_b32_e32 v20, v88
	v_mov_b32_e32 v21, v88
	v_mov_b32_e32 v22, v88
	v_mov_b32_e32 v23, v88
	v_mov_b32_e32 v24, v88
	v_mov_b32_e32 v25, v88
	v_mov_b32_e32 v26, v88
	v_mov_b32_e32 v27, v88
	v_mov_b32_e32 v28, v88
	v_mov_b32_e32 v29, v88
	v_mov_b32_e32 v30, v88
	v_mov_b32_e32 v31, v88
	v_mov_b32_e32 v32, v88
	v_mov_b32_e32 v33, v88
	v_mov_b32_e32 v34, v88
	v_mov_b32_e32 v35, v88
	v_mov_b32_e32 v36, v88
	v_mov_b32_e32 v37, v88
	v_mov_b32_e32 v38, v88
	v_mov_b32_e32 v39, v88
	v_mov_b32_e32 v40, v88
	v_mov_b32_e32 v41, v88
	v_mov_b32_e32 v42, v88
	v_mov_b32_e32 v43, v88
	v_mov_b32_e32 v44, v88
	v_mov_b32_e32 v45, v88
	v_mov_b32_e32 v46, v88
	v_mov_b32_e32 v47, v88
	v_mov_b32_e32 v48, v88
	v_mov_b32_e32 v49, v88
	v_mov_b32_e32 v50, v88
	v_mov_b32_e32 v51, v88
	v_mov_b32_e32 v52, v88
	v_mov_b32_e32 v53, v88
	v_mov_b32_e32 v54, v88
	v_mov_b32_e32 v55, v88
	v_mov_b32_e32 v56, v88
	v_mov_b32_e32 v57, v88
	v_mov_b32_e32 v58, v88
	v_mov_b32_e32 v59, v88
	v_mov_b32_e32 v60, v88
	v_mov_b32_e32 v61, v88
	v_mov_b32_e32 v62, v88
	v_mov_b32_e32 v63, v88
	v_mov_b32_e32 v64, v88
	v_mov_b32_e32 v65, v88
	v_mov_b32_e32 v66, v88
	v_mov_b32_e32 v67, v88
	v_mov_b32_e32 v68, v88
	v_mov_b32_e32 v69, v88
	v_mov_b32_e32 v70, v88
	v_mov_b32_e32 v71, v88
	v_mov_b32_e32 v72, v88
	v_mov_b32_e32 v73, v88
	v_mov_b32_e32 v74, v88
	v_mov_b32_e32 v75, v88
	v_mov_b32_e32 v76, v88
	v_mov_b32_e32 v77, v88
	v_mov_b32_e32 v78, v88
	v_mov_b32_e32 v79, v88
	v_mov_b32_e32 v80, v88
	v_mov_b32_e32 v81, v88
	v_mov_b32_e32 v82, v88
	v_mov_b32_e32 v83, v88
	v_mov_b32_e32 v84, v88
	v_mov_b32_e32 v85, v88
	v_mov_b32_e32 v86, v88
	v_mov_b32_e32 v87, v88
	v_mov_b32_e32 v92, v88
	v_mov_b32_e32 v93, v88
	v_mov_b32_e32 v94, v88
	v_mov_b32_e32 v95, v88
	v_mov_b32_e32 v96, v88
	v_mov_b32_e32 v97, v88
	v_mov_b32_e32 v98, v88
	v_mov_b32_e32 v99, v88
	v_mov_b32_e32 v100, v88
	v_mov_b32_e32 v101, v88
	v_mov_b32_e32 v102, v88
	v_mov_b32_e32 v103, v88
	v_mov_b32_e32 v104, v88
	v_mov_b32_e32 v105, v88
	v_mov_b32_e32 v106, v88
	v_mov_b32_e32 v107, v88
	v_mov_b32_e32 v108, v88
	v_mov_b32_e32 v109, v88
	v_mov_b32_e32 v110, v88
	v_mov_b32_e32 v111, v88
	v_mov_b32_e32 v112, v88
	v_mov_b32_e32 v113, v88
	v_mov_b32_e32 v114, v88
	v_mov_b32_e32 v115, v88
	v_mov_b32_e32 v116, v88
	v_mov_b32_e32 v117, v88
	v_mov_b32_e32 v118, v88
	v_mov_b32_e32 v119, v88
	v_mov_b32_e32 v120, v88
	v_mov_b32_e32 v121, v88
	v_mov_b32_e32 v122, v88
	v_mov_b32_e32 v123, v88
	v_mov_b32_e32 v124, v88
	v_mov_b32_e32 v125, v88
	v_mov_b32_e32 v126, v88
	v_mov_b32_e32 v127, v88
	s_waitcnt vmcnt(0) lgkmcnt(0)
	s_barrier
	s_bitcmp1_b32 s3, 12
	s_cbranch_scc0 .Lkb_500

.LBB0_669:
	v_lshlrev_b64 v[132:133], 10, v[0:1]
	v_and_b32_e32 v0, 15, v2
	v_and_b32_e32 v1, 3, v3
	v_lshrrev_b32_e32 v3, 1, v2
	s_mov_b32 s2, 0x1ffff80
	v_and_or_b32 v0, v3, s2, v0
	v_lshlrev_b32_e32 v134, 7, v0
	v_bfe_u32 v0, v2, 1, 3
	v_bitop3_b32 v0, v1, v0, 4 bitop3:0x36
	v_lshlrev_b32_e32 v135, 4, v0
	v_lshlrev_b32_e32 v0, 7, v2
	s_waitcnt vmcnt(0)
	v_bitop3_b32 v3, v3, v1, 7 bitop3:0x6c
	v_and_b32_e32 v136, 0x6780, v0
	v_mov_b32_e32 v0, 0
	v_lshlrev_b32_e32 v137, 4, v3
	s_mov_b64 s[34:35], 0
	s_mov_b32 s2, 0
	v_mov_b32_e32 v1, v0
	v_mov_b32_e32 v2, v0
	v_mov_b32_e32 v3, v0
	v_mov_b32_e32 v4, v0
	v_mov_b32_e32 v5, v0
	v_mov_b32_e32 v6, v0
	v_mov_b32_e32 v7, v0
	v_mov_b32_e32 v8, v0
	v_mov_b32_e32 v9, v0
	v_mov_b32_e32 v10, v0
	v_mov_b32_e32 v11, v0
	v_mov_b32_e32 v12, v0
	v_mov_b32_e32 v13, v0
	v_mov_b32_e32 v14, v0
	v_mov_b32_e32 v15, v0
	v_mov_b32_e32 v16, v0
	v_mov_b32_e32 v17, v0
	v_mov_b32_e32 v18, v0
	v_mov_b32_e32 v19, v0
	v_mov_b32_e32 v20, v0
	v_mov_b32_e32 v21, v0
	v_mov_b32_e32 v22, v0
	v_mov_b32_e32 v23, v0
	v_mov_b32_e32 v24, v0
	v_mov_b32_e32 v25, v0
	v_mov_b32_e32 v26, v0
	v_mov_b32_e32 v27, v0
	v_mov_b32_e32 v28, v0
	v_mov_b32_e32 v29, v0
	v_mov_b32_e32 v30, v0
	v_mov_b32_e32 v31, v0
	v_mov_b32_e32 v32, v0
	v_mov_b32_e32 v33, v0
	v_mov_b32_e32 v34, v0
	v_mov_b32_e32 v35, v0
	v_mov_b32_e32 v36, v0
	v_mov_b32_e32 v37, v0
	v_mov_b32_e32 v38, v0
	v_mov_b32_e32 v39, v0
	v_mov_b32_e32 v44, v0
	v_mov_b32_e32 v45, v0
	v_mov_b32_e32 v46, v0
	v_mov_b32_e32 v47, v0
	v_mov_b32_e32 v56, v0
	v_mov_b32_e32 v57, v0
	v_mov_b32_e32 v58, v0
	v_mov_b32_e32 v59, v0
	v_mov_b32_e32 v68, v0
	v_mov_b32_e32 v69, v0
	v_mov_b32_e32 v70, v0
	v_mov_b32_e32 v71, v0
	v_mov_b32_e32 v76, v0
	v_mov_b32_e32 v77, v0
	v_mov_b32_e32 v78, v0
	v_mov_b32_e32 v79, v0
	v_mov_b32_e32 v88, v0
	v_mov_b32_e32 v89, v0
	v_mov_b32_e32 v90, v0
	v_mov_b32_e32 v91, v0
	v_mov_b32_e32 v100, v0
	v_mov_b32_e32 v101, v0
	v_mov_b32_e32 v102, v0
	v_mov_b32_e32 v103, v0
	v_mov_b32_e32 v108, v0
	v_mov_b32_e32 v109, v0
	v_mov_b32_e32 v110, v0
	v_mov_b32_e32 v111, v0
	v_mov_b32_e32 v116, v0
	v_mov_b32_e32 v117, v0
	v_mov_b32_e32 v118, v0
	v_mov_b32_e32 v119, v0
	v_mov_b32_e32 v40, v0
	v_mov_b32_e32 v41, v0
	v_mov_b32_e32 v42, v0
	v_mov_b32_e32 v43, v0
	v_mov_b32_e32 v48, v0
	v_mov_b32_e32 v49, v0
	v_mov_b32_e32 v50, v0
	v_mov_b32_e32 v51, v0
	v_mov_b32_e32 v52, v0
	v_mov_b32_e32 v53, v0
	v_mov_b32_e32 v54, v0
	v_mov_b32_e32 v55, v0
	v_mov_b32_e32 v60, v0
	v_mov_b32_e32 v61, v0
	v_mov_b32_e32 v62, v0
	v_mov_b32_e32 v63, v0
	v_mov_b32_e32 v64, v0
	v_mov_b32_e32 v65, v0
	v_mov_b32_e32 v66, v0
	v_mov_b32_e32 v67, v0
	v_mov_b32_e32 v72, v0
	v_mov_b32_e32 v73, v0
	v_mov_b32_e32 v74, v0
	v_mov_b32_e32 v75, v0
	v_mov_b32_e32 v80, v0
	v_mov_b32_e32 v81, v0
	v_mov_b32_e32 v82, v0
	v_mov_b32_e32 v83, v0
	v_mov_b32_e32 v84, v0
	v_mov_b32_e32 v85, v0
	v_mov_b32_e32 v86, v0
	v_mov_b32_e32 v87, v0
	v_mov_b32_e32 v92, v0
	v_mov_b32_e32 v93, v0
	v_mov_b32_e32 v94, v0
	v_mov_b32_e32 v95, v0
	v_mov_b32_e32 v96, v0
	v_mov_b32_e32 v97, v0
	v_mov_b32_e32 v98, v0
	v_mov_b32_e32 v99, v0
	v_mov_b32_e32 v104, v0
	v_mov_b32_e32 v105, v0
	v_mov_b32_e32 v106, v0
	v_mov_b32_e32 v107, v0
	v_mov_b32_e32 v112, v0
	v_mov_b32_e32 v113, v0
	v_mov_b32_e32 v114, v0
	v_mov_b32_e32 v115, v0
	v_mov_b32_e32 v120, v0
	v_mov_b32_e32 v121, v0
	v_mov_b32_e32 v122, v0
	v_mov_b32_e32 v123, v0
	v_mov_b32_e32 v124, v0
	v_mov_b32_e32 v125, v0
	v_mov_b32_e32 v126, v0
	v_mov_b32_e32 v127, v0
	s_waitcnt vmcnt(0) lgkmcnt(0)
	s_barrier
	s_bitcmp1_b32 s0, 12
	s_cbranch_scc0 .Lkb_670
